# overlap v5: also run the HGRN output-projection GEMM on the 192 non-recurrence workgroups, gated per row-tile pair on recurrence progress counters; recurrence output stored write-through
# baseline (speedup 1.0000x reference)
.LBB0_353:
	s_waitcnt vmcnt(0)
	s_barrier
	v_readfirstlane_b32 s99, v208
	s_lshr_b32 s99, s99, 6
	s_cmp_lg_u32 s99, 0
	s_cbranch_scc1 .Lh2e_skip
	s_lshr_b32 s99, s70, 3
	s_lshl_b32 s99, s99, 4
	s_add_u32 s99, s99, 15
	s_lshl_b32 s99, s99, 2
	s_add_u32 s99, s99, 0x3600
	v_mov_b32_e32 v253, s99
	v_mov_b32_e32 v254, 1
	s_mov_b64 s[100:101], exec
	s_mov_b64 exec, 1
	global_atomic_add v253, v254, s[74:75]
	s_mov_b64 exec, s[100:101]

.LBB0_471:
	s_or_b64 exec, exec, s[30:31]
	s_waitcnt lgkmcnt(0)
	s_barrier
	ds_read_b128 v[88:91], v117
	ds_read_b128 v[92:95], v117 offset:256
	s_mov_b32 s30, 0x35000000
	v_add_u32_e32 v170, v116, v141
	s_waitcnt lgkmcnt(0)
	v_pk_add_f32 v[88:89], v[88:89], v[92:93]
	v_mov_b64_e32 v[92:93], s[66:67]
	v_pk_fma_f32 v[88:89], v[88:89], s[60:61], v[92:93] op_sel_hi:[1,0,0]
	s_nop 0
	v_mul_f32_e32 v158, 0x4b800000, v88
	v_cmp_gt_f32_e32 vcc, s90, v88
	s_nop 1
	v_cndmask_b32_e32 v88, v88, v158, vcc
	v_rsq_f32_e32 v88, v88
	s_nop 0
	v_mul_f32_e32 v158, 0x45800000, v88
	v_cndmask_b32_e32 v88, v88, v158, vcc
	v_mul_f32_e32 v72, v72, v88
	v_mul_f32_e32 v72, v108, v72
	v_mul_f32_e32 v76, v76, v88
	v_cvt_pk_bf16_f32 v72, v72, s0
	ds_write_b16 v153, v72
	v_mul_f32_e32 v72, v109, v76
	v_cvt_pk_bf16_f32 v72, v72, s0
	ds_write_b16 v153, v72 offset:32
	v_mul_f32_e32 v72, v80, v88
	v_mul_f32_e32 v76, 0x4b800000, v89
	v_cmp_gt_f32_e32 vcc, s90, v89
	v_mul_f32_e32 v72, v110, v72
	v_cvt_pk_bf16_f32 v72, v72, s0
	v_cndmask_b32_e32 v76, v89, v76, vcc
	v_rsq_f32_e32 v76, v76
	ds_write_b16 v153, v72 offset:64
	v_mul_f32_e32 v72, v84, v88
	v_mul_f32_e32 v72, v111, v72
	v_cvt_pk_bf16_f32 v72, v72, s0
	ds_write_b16 v153, v72 offset:96
	v_mul_f32_e32 v72, 0x45800000, v76
	v_cndmask_b32_e32 v72, v76, v72, vcc
	v_mul_f32_e32 v73, v73, v72
	v_mul_f32_e32 v73, v108, v73
	v_cvt_pk_bf16_f32 v73, v73, s0
	ds_write_b16 v153, v73 offset:144
	v_mul_f32_e32 v73, v77, v72
	v_mul_f32_e32 v73, v109, v73
	v_cvt_pk_bf16_f32 v73, v73, s0
	ds_write_b16 v153, v73 offset:176
	v_mul_f32_e32 v73, v81, v72
	v_mul_f32_e32 v73, v110, v73
	v_cvt_pk_bf16_f32 v73, v73, s0
	ds_write_b16 v153, v73 offset:208
	v_mul_f32_e32 v76, v85, v72
	v_pk_add_f32 v[72:73], v[90:91], v[94:95]
	v_mul_f32_e32 v76, v111, v76
	v_pk_fma_f32 v[72:73], v[72:73], s[60:61], v[92:93] op_sel_hi:[1,0,0]
	v_cvt_pk_bf16_f32 v76, v76, s0
	v_mul_f32_e32 v77, 0x4b800000, v72
	v_cmp_gt_f32_e32 vcc, s90, v72
	ds_write_b16 v153, v76 offset:240
	v_add_u32_e32 v158, s92, v115
	v_cndmask_b32_e32 v72, v72, v77, vcc
	v_rsq_f32_e32 v72, v72
	s_nop 0
	v_mul_f32_e32 v76, 0x45800000, v72
	v_cndmask_b32_e32 v72, v72, v76, vcc
	v_mul_f32_e32 v74, v74, v72
	v_mul_f32_e32 v74, v108, v74
	v_cvt_pk_bf16_f32 v74, v74, s0
	ds_write_b16 v153, v74 offset:288
	v_mul_f32_e32 v74, v78, v72
	v_mul_f32_e32 v74, v109, v74
	v_cvt_pk_bf16_f32 v74, v74, s0
	ds_write_b16 v153, v74 offset:320
	v_mul_f32_e32 v74, v82, v72
	v_mul_f32_e32 v74, v110, v74
	v_cvt_pk_bf16_f32 v74, v74, s0
	ds_write_b16 v153, v74 offset:352
	v_mul_f32_e32 v74, 0x4b800000, v73
	v_cmp_gt_f32_e32 vcc, s90, v73
	v_mul_f32_e32 v72, v86, v72
	v_mul_f32_e32 v72, v111, v72
	v_cndmask_b32_e32 v73, v73, v74, vcc
	v_rsq_f32_e32 v73, v73
	v_cvt_pk_bf16_f32 v72, v72, s0
	ds_write_b16 v153, v72 offset:384
	v_lshlrev_b32_e32 v82, 16, v68
	v_mul_f32_e32 v72, 0x45800000, v73
	v_cndmask_b32_e32 v72, v73, v72, vcc
	v_mul_f32_e32 v73, v75, v72
	v_mul_f32_e32 v73, v108, v73
	v_cvt_pk_bf16_f32 v73, v73, s0
	ds_write_b16 v153, v73 offset:432
	v_mul_f32_e32 v73, v79, v72
	v_mul_f32_e32 v73, v109, v73
	v_cvt_pk_bf16_f32 v73, v73, s0
	ds_write_b16 v153, v73 offset:464
	v_mul_f32_e32 v73, v83, v72
	v_mul_f32_e32 v72, v87, v72
	v_mul_f32_e32 v73, v110, v73
	v_mul_f32_e32 v72, v111, v72
	v_cvt_pk_bf16_f32 v73, v73, s0
	v_cvt_pk_bf16_f32 v72, v72, s0
	ds_write_b16 v153, v73 offset:496
	ds_write_b16 v153, v72 offset:528
	s_waitcnt lgkmcnt(0)
	ds_read_b128 v[72:75], v140
	ds_read_b128 v[76:79], v140 offset:64
	v_and_b32_e32 v83, 0xffff0000, v68
	s_waitcnt lgkmcnt(1)
	v_lshlrev_b32_e32 v80, 16, v72
	v_and_b32_e32 v81, 0xffff0000, v72
	v_pk_mul_f32 v[80:81], v[82:83], v[80:81]
	v_lshlrev_b32_e32 v72, 16, v73
	v_cvt_pk_bf16_f32 v68, v80, v81
	v_and_b32_e32 v73, 0xffff0000, v73
	v_lshlrev_b32_e32 v80, 16, v69
	v_and_b32_e32 v81, 0xffff0000, v69
	v_pk_mul_f32 v[72:73], v[80:81], v[72:73]
	v_lshlrev_b32_e32 v80, 16, v70
	v_cvt_pk_bf16_f32 v69, v72, v73
	v_lshlrev_b32_e32 v72, 16, v74
	v_and_b32_e32 v73, 0xffff0000, v74
	v_and_b32_e32 v81, 0xffff0000, v70
	v_pk_mul_f32 v[72:73], v[80:81], v[72:73]
	v_lshlrev_b32_e32 v74, 16, v71
	v_cvt_pk_bf16_f32 v70, v72, v73
	v_lshlrev_b32_e32 v72, 16, v75
	v_and_b32_e32 v73, 0xffff0000, v75
	v_and_b32_e32 v75, 0xffff0000, v71
	v_pk_mul_f32 v[72:73], v[74:75], v[72:73]
	s_nop 0
	v_cvt_pk_bf16_f32 v71, v72, v73
	v_lshl_add_u64 v[72:73], v[98:99], 0, s[86:87]
	v_add_co_u32_e32 v72, vcc, s30, v72
	s_nop 1
	v_addc_co_u32_e32 v73, vcc, 0, v73, vcc
	global_store_dwordx4 v[72:73], v[68:71], off sc1
	s_waitcnt lgkmcnt(0)
	s_nop 0
	v_lshlrev_b32_e32 v68, 16, v76
	v_and_b32_e32 v69, 0xffff0000, v76
	v_lshlrev_b32_e32 v70, 16, v56
	v_and_b32_e32 v71, 0xffff0000, v56
	v_pk_mul_f32 v[68:69], v[70:71], v[68:69]
	v_lshlrev_b32_e32 v70, 16, v57
	v_cvt_pk_bf16_f32 v56, v68, v69
	v_lshlrev_b32_e32 v68, 16, v77
	v_and_b32_e32 v69, 0xffff0000, v77
	v_and_b32_e32 v71, 0xffff0000, v57
	v_pk_mul_f32 v[68:69], v[70:71], v[68:69]
	v_lshlrev_b32_e32 v70, 16, v58
	v_cvt_pk_bf16_f32 v57, v68, v69
	v_lshlrev_b32_e32 v68, 16, v78
	v_and_b32_e32 v69, 0xffff0000, v78
	v_and_b32_e32 v71, 0xffff0000, v58
	v_pk_mul_f32 v[68:69], v[70:71], v[68:69]
	v_lshlrev_b32_e32 v70, 16, v59
	v_cvt_pk_bf16_f32 v58, v68, v69
	v_lshlrev_b32_e32 v68, 16, v79
	v_and_b32_e32 v69, 0xffff0000, v79
	v_and_b32_e32 v71, 0xffff0000, v59
	v_pk_mul_f32 v[68:69], v[70:71], v[68:69]
	s_nop 0
	v_cvt_pk_bf16_f32 v59, v68, v69
	global_store_dwordx4 v[72:73], v[56:59], off offset:64 sc1
	s_waitcnt lgkmcnt(0)
	ds_read_b128 v[56:59], v154 offset:34816
	ds_read_b128 v[68:71], v154 offset:34880
	ds_read_b128 v[72:75], v170 offset:53248
	ds_read_b128 v[76:79], v170 offset:53312
	ds_read_b128 v[80:83], v170 offset:55552
	ds_read_b128 v[84:87], v170 offset:55616
	ds_read_b128 v[88:91], v170 offset:57856
	ds_read_b128 v[92:95], v170 offset:57920
	ds_read_b128 v[158:161], v158
	ds_read_b128 v[162:165], v170 offset:60160
	ds_read_b128 v[166:169], v170 offset:60224
	s_waitcnt lgkmcnt(2)
	v_pk_mul_f32 v[24:25], v[24:25], v[158:159]
	v_pk_mul_f32 v[26:27], v[26:27], v[160:161]
	v_pk_mul_f32 v[32:33], v[32:33], v[158:159]
	v_pk_mul_f32 v[34:35], v[34:35], v[160:161]
	v_mfma_f32_16x16x32_bf16 v[24:27], v[56:59], v[72:75], v[24:27]
	v_mul_f32_e64 v40, v40, v158
	v_mul_f32_e64 v41, v41, v159
	v_pk_mul_f32 v[42:43], v[42:43], v[160:161]
	v_pk_mul_f32 v[44:45], v[44:45], v[158:159]
	v_mfma_f32_16x16x32_bf16 v[32:35], v[56:59], v[80:83], v[32:35]
	v_mul_f32_e64 v46, v46, v160
	v_mul_f32_e64 v47, v47, v161
	v_mfma_f32_16x16x32_bf16 v[40:43], v[56:59], v[88:91], v[40:43]
	s_waitcnt lgkmcnt(1)
	v_mfma_f32_16x16x32_bf16 v[44:47], v[56:59], v[162:165], v[44:47]
	v_mfma_f32_16x16x32_bf16 v[24:27], v[68:71], v[76:79], v[24:27]
	v_mfma_f32_16x16x32_bf16 v[32:35], v[68:71], v[84:87], v[32:35]
	v_mfma_f32_16x16x32_bf16 v[40:43], v[68:71], v[92:95], v[40:43]
	s_nop 5
	v_cvt_pk_bf16_f32 v72, v24, v25
	v_cvt_pk_bf16_f32 v73, v26, v27
	ds_write_b64 v155, v[72:73]
	s_waitcnt lgkmcnt(1)
	v_mfma_f32_16x16x32_bf16 v[44:47], v[68:71], v[166:169], v[44:47]
	v_cvt_pk_bf16_f32 v72, v32, v33
	v_cvt_pk_bf16_f32 v73, v34, v35
	ds_write_b64 v155, v[72:73] offset:4352
	v_cvt_pk_bf16_f32 v72, v40, v41
	v_cvt_pk_bf16_f32 v73, v42, v43
	ds_write_b64 v155, v[72:73] offset:8704
	s_nop 1
	v_cvt_pk_bf16_f32 v72, v44, v45
	v_cvt_pk_bf16_f32 v73, v46, v47
	ds_write_b64 v155, v[72:73] offset:13056
	ds_read_b128 v[72:75], v170 offset:62464
	ds_read_b128 v[76:79], v170 offset:62528
	ds_read_b128 v[80:83], v170 offset:64768
	ds_read_b128 v[84:87], v170 offset:64832
	ds_read_b128 v[88:91], v142 offset:13824
	ds_read_b128 v[92:95], v142 offset:13888
	ds_read_b128 v[162:165], v142 offset:16128
	ds_read_b128 v[166:169], v142 offset:16192
	v_pk_mul_f32 v[48:49], v[48:49], v[158:159]
	v_pk_mul_f32 v[50:51], v[50:51], v[160:161]
	v_pk_mul_f32 v[52:53], v[52:53], v[158:159]
	v_pk_mul_f32 v[54:55], v[54:55], v[160:161]
	s_waitcnt lgkmcnt(3)
	v_mfma_f32_16x16x32_bf16 v[48:51], v[56:59], v[88:91], v[48:51]
	v_mul_f32_e64 v28, v28, v158
	v_mul_f32_e64 v29, v29, v159
	v_pk_mul_f32 v[30:31], v[30:31], v[160:161]
	v_pk_mul_f32 v[36:37], v[36:37], v[158:159]
	s_waitcnt lgkmcnt(1)
	v_mfma_f32_16x16x32_bf16 v[52:55], v[56:59], v[162:165], v[52:55]
	v_mul_f32_e64 v38, v38, v160
	v_mul_f32_e64 v39, v39, v161
	s_mov_b64 s[30:31], 0x20000
	s_add_i32 s71, s71, -1
	v_mfma_f32_16x16x32_bf16 v[28:31], v[56:59], v[72:75], v[28:31]
	v_lshl_add_u64 v[98:99], v[98:99], 0, s[30:31]
	v_lshl_add_u64 v[100:101], v[100:101], 0, s[68:69]
	v_lshl_add_u64 v[102:103], v[102:103], 0, s[68:69]
	v_mfma_f32_16x16x32_bf16 v[36:39], v[56:59], v[80:83], v[36:39]
	v_lshl_add_u64 v[104:105], v[104:105], 0, s[68:69]
	s_cmp_lg_u32 s71, -1
	v_mfma_f32_16x16x32_bf16 v[48:51], v[68:71], v[92:95], v[48:51]
	s_waitcnt lgkmcnt(0)
	v_mfma_f32_16x16x32_bf16 v[52:55], v[68:71], v[166:169], v[52:55]
	v_mfma_f32_16x16x32_bf16 v[28:31], v[68:71], v[76:79], v[28:31]
	s_nop 4
	v_cvt_pk_bf16_f32 v56, v48, v49
	v_cvt_pk_bf16_f32 v57, v50, v51
	ds_write_b64 v155, v[56:57] offset:26112
	v_mfma_f32_16x16x32_bf16 v[36:39], v[68:71], v[84:87], v[36:39]
	v_cvt_pk_bf16_f32 v56, v52, v53
	v_cvt_pk_bf16_f32 v57, v54, v55
	v_cvt_pk_bf16_f32 v72, v28, v29
	v_cvt_pk_bf16_f32 v73, v30, v31
	ds_write_b64 v155, v[56:57] offset:30464
	s_waitcnt vmcnt(3)
	v_mov_b64_e32 v[70:71], v[62:63]
	s_waitcnt vmcnt(2)
	v_mov_b64_e32 v[56:57], v[64:65]
	ds_write_b64 v155, v[72:73] offset:17408
	v_cvt_pk_bf16_f32 v72, v36, v37
	v_cvt_pk_bf16_f32 v73, v38, v39
	v_mov_b64_e32 v[68:69], v[60:61]
	v_mov_b64_e32 v[58:59], v[66:67]
	ds_write_b64 v155, v[72:73] offset:21760
	s_cbranch_scc0 .LBB0_353
.LBB0_472:
	s_and_b32 s98, s71, 3
	s_cmp_lg_u32 s98, 3
	s_cbranch_scc1 .Lh2_skip
	s_cmp_eq_u32 s71, 0x7f
	s_cbranch_scc1 .Lh2_skip
	s_waitcnt vmcnt(0)
	s_barrier
	v_readfirstlane_b32 s99, v208
	s_lshr_b32 s99, s99, 6
	s_cmp_lg_u32 s99, 0
	s_cbranch_scc1 .Lh2_skip
	s_sub_u32 s99, 0x7e, s71
	s_lshr_b32 s99, s99, 3
	s_lshr_b32 s100, s70, 3
	s_lshl_b32 s100, s100, 4
	s_add_u32 s99, s99, s100
	s_lshl_b32 s99, s99, 2
	s_add_u32 s99, s99, 0x3600
	v_mov_b32_e32 v253, s99
	v_mov_b32_e32 v254, 1
	s_mov_b64 s[100:101], exec
	s_mov_b64 exec, 1
	global_atomic_add v253, v254, s[74:75]
	s_mov_b64 exec, s[100:101]

.LBB0_488:
	s_cmpk_lt_u32 s3, 64
	s_cbranch_scc1 .Lov2_hgrn_exit
	s_branch .Lov2_p1wg
	s_waitcnt vmcnt(0)
	s_barrier
	s_mov_b64 s[0:1], exec
	v_readlane_b32 s4, v252, 0
	v_readlane_b32 s5, v252, 1
	s_and_b64 s[4:5], s[0:1], s[4:5]
	s_mov_b64 exec, s[4:5]
	s_cbranch_execz .LBB0_540
	s_add_i32 s4, 0, 0x25e00
	v_mov_b32_e32 v0, s4
	s_waitcnt vmcnt(0) expcnt(0) lgkmcnt(0)
	ds_read_b32 v2, v0
	s_add_i32 s4, 0, 0x25e04
	v_mov_b32_e32 v0, s4
	ds_read_b32 v0, v0
	s_waitcnt lgkmcnt(1)
	v_cmp_ne_u32_e32 vcc, 0, v2
	s_cbranch_vccnz .LBB0_504
	v_readlane_b32 s4, v252, 2
	s_mul_i32 s18, s79, s4
	s_add_u32 s4, s74, 0x1000
	s_addc_u32 s5, s75, 0
	s_add_u32 s6, s74, 0x1100
	s_addc_u32 s7, s75, 0
	s_add_u32 s8, s74, 0x1200
	s_addc_u32 s9, s75, 0
	s_add_u32 s10, s74, 0x1300
	s_mul_i32 s18, s18, s78
	s_addc_u32 s11, s75, 0
	s_mov_b32 s19, 1
	v_mov_b32_e32 v16, 0
	s_branch .LBB0_492

.Lov2_hgrn_exit:
	v_readlane_b32 s84, v252, 20
	v_readlane_b32 s82, v252, 18
	v_readlane_b32 s86, v252, 16
	v_readlane_b32 s85, v252, 21
	v_readlane_b32 s83, v252, 19
	v_readlane_b32 s87, v252, 17
	s_add_u32 s12, s74, 0xc400000
	s_addc_u32 s13, s75, 0
	s_add_u32 s10, s74, 0x3d200000
	s_addc_u32 s11, s75, 0
	s_mov_b64 s[4:5], 0
	s_branch .LBB0_648
.Lov2_p1wg:
	s_waitcnt vmcnt(0)
	s_barrier
	v_mov_b32_e32 v253, 0x3c40
	v_readfirstlane_b32 s99, v208
	s_lshr_b32 s99, s99, 6
	s_cmp_lg_u32 s99, 0
	s_cbranch_scc1 .Lov2_c5_nosig
	buffer_wbl2 sc1
	s_waitcnt vmcnt(0)
	v_mov_b32_e32 v254, 1
	s_mov_b64 s[100:101], exec
	s_mov_b64 exec, 1
	global_atomic_add v253, v254, s[74:75]
	s_mov_b64 exec, s[100:101]

.Lspin_join_c5:
.Lov2_p3_entry:
	v_mov_b32_e32 v8, v208
	s_cmpk_lt_i32 s3, 0x410
	v_readlane_b32 s84, v252, 20
	v_readlane_b32 s82, v252, 18
	v_readlane_b32 s86, v252, 16
	s_waitcnt lgkmcnt(0)
	s_barrier
	s_cselect_b64 s[0:1], -1, 0
	s_cmpk_gt_i32 s3, 0x40f
	v_readfirstlane_b32 s18, v8
	v_readlane_b32 s85, v252, 21
	v_readlane_b32 s83, v252, 19
	v_readlane_b32 s87, v252, 17
	s_cbranch_scc1 .LBB0_549
	s_cmpk_lt_i32 s3, 0x400
	s_cbranch_scc1 .LBB0_543
	s_lshl_b32 s5, s3, 6
	s_and_b32 s4, s3, 3
	s_and_b32 s5, s5, 0x3f00
	s_or_b32 s4, s5, s4
	s_add_i32 s30, s4, 0x100
	s_movk_i32 s8, 0x100
	s_cbranch_execz .LBB0_544
	s_branch .LBB0_549

.LBB0_549:
	s_sub_u32 s6, s3, 64
	s_cmpk_lt_u32 s6, 0x400
	s_cbranch_scc0 .Lm3_piece_first
	s_lshr_b32 s8, s6, 5
	s_and_b32 s7, s6, 7
	s_lshl_b32 s7, s7, 5
	s_add_u32 s8, s8, s7
	s_bfe_u32 s30, s6, 0x20003
	s_branch .Lm3_done_first
.Lm3_piece_first:
	s_sub_u32 s7, s6, 0x400
	s_lshr_b32 s30, s7, 2
	s_add_u32 s30, s30, 1
	s_lshl_b32 s30, s30, 8
	s_and_b32 s7, s7, 3
	s_or_b32 s30, s30, s7
	s_movk_i32 s8, 0x100
.Lm3_done_first:
	s_mov_b64 s[0:1], -1
	s_cmpk_lt_u32 s8, 0x100
	s_cbranch_scc0 .Lp3_skip_f
	s_lshr_b32 s100, s8, 1
	s_lshl_b32 s100, s100, 2
	s_add_u32 s100, s100, 0x3600
	v_mov_b32_e32 v253, s100
	v_readfirstlane_b32 s99, v208
	s_lshr_b32 s99, s99, 6
	s_cmp_lg_u32 s99, 0
	s_cbranch_scc1 .Lspin_join_p3f
	s_mov_b32 s99, 0
.Lspin_p3f:
	global_load_dword v254, v253, s[74:75] sc1
	s_waitcnt vmcnt(0)
	v_readfirstlane_b32 s100, v254
	s_cmp_ge_u32 s100, 0x10
	s_cbranch_scc1 .Lspin_done_p3f
	s_sleep 24
	s_add_u32 s99, s99, 1
	s_cmp_lt_u32 s99, 0x2000
	s_cbranch_scc1 .Lspin_p3f

.Lspin_join_p3f:
	s_barrier
.Lp3_skip_f:
	s_add_u32 s12, s74, 0xc400000
	s_addc_u32 s13, s75, 0
	s_add_u32 s10, s74, 0x3d200000
	v_cndmask_b32_e64 v0, 0, 1, s[0:1]
	s_addc_u32 s11, s75, 0
	v_cmp_ne_u32_e64 s[4:5], 1, v0
	s_andn2_b64 vcc, exec, s[0:1]
	s_cbranch_vccnz .LBB0_648
	s_cmpk_lt_u32 s30, 0x100
	s_cselect_b64 s[0:1], -1, 0
	s_cmpk_gt_u32 s30, 0xff
	s_cselect_b64 s[16:17], -1, 0
	s_mov_b64 s[6:7], 0
	s_and_b64 vcc, exec, s[0:1]
	s_mov_b64 s[14:15], 0
	s_cbranch_vccnz .LBB0_552
	s_ashr_i32 s9, s30, 6
	s_and_b32 s14, s9, -4
	s_ashr_i32 s15, s14, 31
	s_lshl_b64 s[14:15], s[14:15], 7
	s_add_u32 s14, s14, 0xfffffe00
	s_addc_u32 s15, s15, -1

.LBB0_568:
	s_mul_i32 s6, s53, 0xc0
	s_add_u32 s6, s6, s3
	s_sub_u32 s6, s6, 64
	s_cmpk_lt_u32 s6, 0x400
	s_cbranch_scc0 .Lm3_piece_next
	s_lshr_b32 s22, s6, 5
	s_and_b32 s7, s6, 7
	s_lshl_b32 s7, s7, 5
	s_add_u32 s22, s22, s7
	s_bfe_u32 s61, s6, 0x20003
	s_branch .Lm3_done_next
.Lm3_piece_next:
	s_sub_u32 s7, s6, 0x400
	s_lshr_b32 s61, s7, 2
	s_add_u32 s61, s61, 1
	s_lshl_b32 s61, s61, 8
	s_and_b32 s7, s7, 3
	s_or_b32 s61, s61, s7
	s_movk_i32 s22, 0x100
.Lm3_done_next:
	s_cmpk_lt_u32 s6, 0x410
	s_cselect_b64 s[0:1], -1, 0
	s_cbranch_scc0 .Lp3_skip_n
	s_cmpk_lt_u32 s22, 0x100
	s_cbranch_scc0 .Lp3_skip_n
	s_lshr_b32 s100, s22, 1
	s_lshl_b32 s100, s100, 2
	s_add_u32 s100, s100, 0x3600
	v_mov_b32_e32 v253, s100
	v_readfirstlane_b32 s99, v208
	s_lshr_b32 s99, s99, 6
	s_cmp_lg_u32 s99, 0
	s_cbranch_scc1 .Lspin_join_p3n
	s_mov_b32 s99, 0

.Lspin_join_p3n:
	s_barrier
.Lp3_skip_n:
	s_nop 0
	v_cndmask_b32_e64 v0, 0, 1, s[0:1]
	v_cmp_ne_u32_e64 s[6:7], 1, v0
	s_andn2_b64 vcc, exec, s[0:1]
	s_mov_b64 s[0:1], s[26:27]
	s_cbranch_vccnz .LBB0_572
	s_cmpk_lt_u32 s61, 0x100
	s_mov_b64 s[0:1], 0
	s_cbranch_scc1 .LBB0_571
	s_ashr_i32 s0, s61, 6
	s_and_b32 s0, s0, -4
	s_ashr_i32 s1, s0, 31
	s_lshl_b64 s[0:1], s[0:1], 7
	s_add_u32 s0, s0, 0xfffffe00
	s_addc_u32 s1, s1, -1
